# SwiGLU activation tile stores write-through (sc1) so that outputs do not occupy L2
# speedup vs baseline: 1.0039x; 1.0039x over previous
; #define PG8_STAGE(bufoff, gbase, voff) do { _Pragma("unroll") for (int _i = 0; _i < 2; ++_i) \
;         __builtin_amdgcn_global_load_lds((const unsigned*)((const char*)(gbase) + (voff)[_i]), (LAS unsigned*)(lds + (bufoff) + ldsw + _i * 8192), 16, 0, 0); } while (0)
; #define PG8_LDA(dst, b, h) do { _Pragma("unroll") for (int m = 0; m < 4; ++m) _Pragma("unroll") for (int k = 0; k < 2; ++k) dst[m][k] = *(const LAS bf16x8*)(lds + PG8_SA(b, h) + aoff + m * 2048 + k * 1024); } while (0)
; #define PG8_LDB(dst, b, h) do { _Pragma("unroll") for (int n = 0; n < 2; ++n) _Pragma("unroll") for (int k = 0; k < 2; ++k) dst[n][k] = *(const LAS bf16x8*)(lds + PG8_SB(b, h) + boff + n * 2048 + k * 1024); } while (0)
; #define PG8_WAIT_V(n) asm volatile("s_waitcnt vmcnt(" #n ")" ::: "memory")
; #define PG8_WAIT_L(n) asm volatile("s_waitcnt lgkmcnt(" #n ")" ::: "memory")
; #define PG8_BAR __builtin_amdgcn_s_barrier()
; #define PG8_SCHED __builtin_amdgcn_sched_barrier(0)
; template <class Epi>
; DI void gemm_phase(LAS unsigned char* lds, int wid, int K, int lda, int ldb, bool bperm, const Sched3& S, const Epi& E) {
;     ...
;             PG8_LDB(B0, 0, 0); PG8_SCHED; PG8_LDA(At, 0, 0); PG8_STAGE(PG8_SA(1, 1), a1 + hA, voffA);
;             PG8_WAIT_L(8); PG8_BAR; PG8_WAIT_L(0); PG8_MMA(0, 0, At, B0); PG8_BAR; PG8_SCHED;
;             PG8_LDB(B1, 0, 1); PG8_STAGE(PG8_SB(0, 0), b2, voffB);
;             PG8_BAR; PG8_WAIT_L(0); PG8_MMA(0, 1, At, B1); PG8_BAR;
;             PG8_LDA(At, 0, 1); PG8_STAGE(PG8_SA(0, 0), a2, voffA);
;             PG8_BAR; PG8_WAIT_L(0); if (full) PG8_MMA(1, 0, At, B0); PG8_BAR; PG8_SCHED;
;             PG8_STAGE(PG8_SB(0, 1), b2 + hstepB, voffB);
;             PG8_WAIT_V(6); PG8_BAR; if (full) PG8_MMA(1, 1, At, B1); PG8_BAR;
;             PG8_LDB(B0, 1, 0); PG8_SCHED; PG8_LDA(At, 1, 0); PG8_STAGE(PG8_SA(0, 1), a2 + h2, voffA);
;             PG8_WAIT_L(8); PG8_BAR; PG8_WAIT_L(0); PG8_MMA(0, 0, At, B0); PG8_BAR; PG8_SCHED;
;             PG8_LDB(B1, 1, 1); PG8_STAGE(PG8_SB(1, 0), b3, voffB);
;             PG8_BAR; PG8_WAIT_L(0); PG8_MMA(0, 1, At, B1); PG8_BAR;
;             PG8_LDA(At, 1, 1); PG8_STAGE(PG8_SA(1, 0), a3, voffA);
;             PG8_BAR; PG8_WAIT_L(0); if (full) PG8_MMA(1, 0, At, B0); PG8_BAR; PG8_SCHED;
;             PG8_STAGE(PG8_SB(1, 1), b3 + hstepB, voffB);
;             PG8_WAIT_V(6); PG8_BAR; if (full) PG8_MMA(1, 1, At, B1); PG8_BAR;
.LBB0_705:
	ds_read_b128 v[138:141], v160
	ds_read_b128 v[142:145], v160 offset:1024
	ds_read_b128 v[146:149], v160 offset:2048
	ds_read_b128 v[150:153], v160 offset:3072
	s_add_u32 s30, s28, 0xfff80080
	s_addc_u32 s31, s29, -1
	s_cmp_eq_u32 s57, 28
	s_cselect_b32 s37, s25, s31
	s_cselect_b32 s36, s24, s30
	s_cselect_b32 s31, s27, s17
	s_cselect_b32 s30, s26, s15
	v_lshl_add_u64 v[156:157], s[28:29], 0, v[132:133]
	s_add_i32 m0, s23, 0xc000
	ds_read_b128 v[164:167], v161
	ds_read_b128 v[168:171], v161 offset:1024
	ds_read_b128 v[172:175], v161 offset:2048
	ds_read_b128 v[176:179], v161 offset:3072
	ds_read_b128 v[180:183], v161 offset:4096
	ds_read_b128 v[184:187], v161 offset:5120
	ds_read_b128 v[188:191], v161 offset:6144
	ds_read_b128 v[192:195], v161 offset:7168
	global_load_lds_dwordx4 v[156:157], off
	v_lshl_add_u64 v[156:157], s[28:29], 0, v[134:135]
	s_add_i32 m0, s23, 0xe000
	s_nop 0
	global_load_lds_dwordx4 v[156:157], off
	s_waitcnt lgkmcnt(8)
	s_barrier
	s_waitcnt lgkmcnt(0)
	s_setprio 1
	s_waitcnt lgkmcnt(0)
	v_mfma_f32_16x16x32_bf16 v[124:127], v[138:141], v[164:167], v[124:127]
	v_mfma_f32_16x16x32_bf16 v[120:123], v[146:149], v[164:167], v[120:123]
	v_mfma_f32_16x16x32_bf16 v[116:119], v[138:141], v[172:175], v[116:119]
	v_mfma_f32_16x16x32_bf16 v[104:107], v[146:149], v[172:175], v[104:107]
	v_mfma_f32_16x16x32_bf16 v[96:99], v[138:141], v[180:183], v[96:99]
	v_mfma_f32_16x16x32_bf16 v[88:91], v[146:149], v[180:183], v[88:91]
	v_mfma_f32_16x16x32_bf16 v[80:83], v[138:141], v[188:191], v[80:83]
	v_mfma_f32_16x16x32_bf16 v[72:75], v[146:149], v[188:191], v[72:75]
	v_mfma_f32_16x16x32_bf16 v[124:127], v[142:145], v[168:171], v[124:127]
	v_mfma_f32_16x16x32_bf16 v[120:123], v[150:153], v[168:171], v[120:123]
	v_mfma_f32_16x16x32_bf16 v[116:119], v[142:145], v[176:179], v[116:119]
	v_mfma_f32_16x16x32_bf16 v[104:107], v[150:153], v[176:179], v[104:107]
	v_mfma_f32_16x16x32_bf16 v[96:99], v[142:145], v[184:187], v[96:99]
	v_mfma_f32_16x16x32_bf16 v[88:91], v[150:153], v[184:187], v[88:91]
	v_mfma_f32_16x16x32_bf16 v[80:83], v[142:145], v[192:195], v[80:83]
	v_mfma_f32_16x16x32_bf16 v[72:75], v[150:153], v[192:195], v[72:75]
	s_setprio 0
	s_barrier
	s_add_i32 s58, s53, s43
	v_lshl_add_u64 v[156:157], s[30:31], 0, v[130:131]
	s_mov_b32 m0, s58
	ds_read_b128 v[196:199], v162
	ds_read_b128 v[200:203], v162 offset:1024
	ds_read_b128 v[204:207], v162 offset:2048
	ds_read_b128 v[208:211], v162 offset:3072
	global_load_lds_dwordx4 v[156:157], off
	v_lshl_add_u64 v[212:213], s[30:31], 0, v[128:129]
	s_add_i32 m0, s58, 0x2000
	s_nop 0
	global_load_lds_dwordx4 v[212:213], off
	s_barrier
	s_waitcnt lgkmcnt(0)
	s_setprio 1
	s_waitcnt lgkmcnt(0)
	v_mfma_f32_16x16x32_bf16 v[112:115], v[196:199], v[164:167], v[112:115]
	v_mfma_f32_16x16x32_bf16 v[108:111], v[204:207], v[164:167], v[108:111]
	v_mfma_f32_16x16x32_bf16 v[100:103], v[196:199], v[172:175], v[100:103]
	v_mfma_f32_16x16x32_bf16 v[92:95], v[204:207], v[172:175], v[92:95]
	v_mfma_f32_16x16x32_bf16 v[84:87], v[196:199], v[180:183], v[84:87]
	v_mfma_f32_16x16x32_bf16 v[76:79], v[204:207], v[180:183], v[76:79]
	v_mfma_f32_16x16x32_bf16 v[68:71], v[196:199], v[188:191], v[68:71]
	v_mfma_f32_16x16x32_bf16 v[64:67], v[204:207], v[188:191], v[64:67]
	v_mfma_f32_16x16x32_bf16 v[112:115], v[200:203], v[168:171], v[112:115]
	v_mfma_f32_16x16x32_bf16 v[108:111], v[208:211], v[168:171], v[108:111]
	v_mfma_f32_16x16x32_bf16 v[100:103], v[200:203], v[176:179], v[100:103]
	v_mfma_f32_16x16x32_bf16 v[92:95], v[208:211], v[176:179], v[92:95]
	v_mfma_f32_16x16x32_bf16 v[84:87], v[200:203], v[184:187], v[84:87]
	v_mfma_f32_16x16x32_bf16 v[76:79], v[208:211], v[184:187], v[76:79]
	v_mfma_f32_16x16x32_bf16 v[68:71], v[200:203], v[192:195], v[68:71]
	v_mfma_f32_16x16x32_bf16 v[64:67], v[208:211], v[192:195], v[64:67]
	s_setprio 0
	s_mov_b32 m0, s23
	v_lshl_add_u64 v[214:215], s[36:37], 0, v[130:131]
	s_barrier
	ds_read_b128 v[164:167], v161 offset:16384
	ds_read_b128 v[168:171], v161 offset:17408
	ds_read_b128 v[172:175], v161 offset:18432
	ds_read_b128 v[176:179], v161 offset:19456
	ds_read_b128 v[180:183], v161 offset:20480
	ds_read_b128 v[184:187], v161 offset:21504
	ds_read_b128 v[188:191], v161 offset:22528
	ds_read_b128 v[192:195], v161 offset:23552
	global_load_lds_dwordx4 v[214:215], off
	v_lshl_add_u64 v[216:217], s[36:37], 0, v[128:129]
	s_mov_b32 m0, s46
	s_nop 0
	global_load_lds_dwordx4 v[216:217], off
	s_barrier
	s_waitcnt lgkmcnt(0)
	s_setprio 1
	s_waitcnt lgkmcnt(0)
	v_mfma_f32_16x16x32_bf16 v[60:63], v[138:141], v[164:167], v[60:63]
	v_mfma_f32_16x16x32_bf16 v[56:59], v[146:149], v[164:167], v[56:59]
	v_mfma_f32_16x16x32_bf16 v[48:51], v[138:141], v[172:175], v[48:51]
	v_mfma_f32_16x16x32_bf16 v[40:43], v[146:149], v[172:175], v[40:43]
	v_mfma_f32_16x16x32_bf16 v[32:35], v[138:141], v[180:183], v[32:35]
	v_mfma_f32_16x16x32_bf16 v[24:27], v[146:149], v[180:183], v[24:27]
	v_mfma_f32_16x16x32_bf16 v[16:19], v[138:141], v[188:191], v[16:19]
	v_mfma_f32_16x16x32_bf16 v[8:11], v[146:149], v[188:191], v[8:11]
	v_mfma_f32_16x16x32_bf16 v[60:63], v[142:145], v[168:171], v[60:63]
	v_mfma_f32_16x16x32_bf16 v[56:59], v[150:153], v[168:171], v[56:59]
	v_mfma_f32_16x16x32_bf16 v[48:51], v[142:145], v[176:179], v[48:51]
	v_mfma_f32_16x16x32_bf16 v[40:43], v[150:153], v[176:179], v[40:43]
	v_mfma_f32_16x16x32_bf16 v[32:35], v[142:145], v[184:187], v[32:35]
	v_mfma_f32_16x16x32_bf16 v[24:27], v[150:153], v[184:187], v[24:27]
	v_mfma_f32_16x16x32_bf16 v[16:19], v[142:145], v[192:195], v[16:19]
	v_mfma_f32_16x16x32_bf16 v[8:11], v[150:153], v[192:195], v[8:11]
	s_setprio 0
	s_barrier
; #define PG8_STAGE(bufoff, gbase, voff) do { _Pragma("unroll") for (int _i = 0; _i < 2; ++_i) \
;         __builtin_amdgcn_global_load_lds((const unsigned*)((const char*)(gbase) + (voff)[_i]), (LAS unsigned*)(lds + (bufoff) + ldsw + _i * 8192), 16, 0, 0); } while (0)
; #define PG8_LDA(dst, b, h) do { _Pragma("unroll") for (int m = 0; m < 4; ++m) _Pragma("unroll") for (int k = 0; k < 2; ++k) dst[m][k] = *(const LAS bf16x8*)(lds + PG8_SA(b, h) + aoff + m * 2048 + k * 1024); } while (0)
; #define PG8_LDB(dst, b, h) do { _Pragma("unroll") for (int n = 0; n < 2; ++n) _Pragma("unroll") for (int k = 0; k < 2; ++k) dst[n][k] = *(const LAS bf16x8*)(lds + PG8_SB(b, h) + boff + n * 2048 + k * 1024); } while (0)
; #define PG8_MMA(ai, bj, At, Bt) do { __builtin_amdgcn_s_setprio(1); _Pragma("unroll") for (int m = 0; m < 4; ++m) _Pragma("unroll") for (int n = 0; n < 2; ++n) _Pragma("unroll") for (int k = 0; k < 2; ++k) \
;         acc[ai][bj][m][n] = __builtin_amdgcn_mfma_f32_16x16x32_bf16(Bt[n][k], At[m][k], acc[ai][bj][m][n], 0, 0, 0); __builtin_amdgcn_s_setprio(0); } while (0)
; #define PG8_WAIT_V(n) asm volatile("s_waitcnt vmcnt(" #n ")" ::: "memory")
; #define PG8_WAIT_L(n) asm volatile("s_waitcnt lgkmcnt(" #n ")" ::: "memory")
; #define PG8_BAR __builtin_amdgcn_s_barrier()
; #define PG8_SCHED __builtin_amdgcn_sched_barrier(0)
; template <class Epi>
; DI void gemm_phase(LAS unsigned char* lds, int wid, int K, int lda, int ldb, bool bperm, const Sched3& S, const Epi& E) {
;     ...
;             PG8_STAGE(PG8_SB(0, 1), b2 + hstepB, voffB);
;             PG8_WAIT_V(6); PG8_BAR; if (full) PG8_MMA(1, 1, At, B1); PG8_BAR;
;             PG8_LDB(B0, 1, 0); PG8_SCHED; PG8_LDA(At, 1, 0); PG8_STAGE(PG8_SA(0, 1), a2 + h2, voffA);
;             PG8_WAIT_L(8); PG8_BAR; PG8_WAIT_L(0); PG8_MMA(0, 0, At, B0); PG8_BAR; PG8_SCHED;
;             PG8_LDB(B1, 1, 1); PG8_STAGE(PG8_SB(1, 0), b3, voffB);
;             PG8_BAR; PG8_WAIT_L(0); PG8_MMA(0, 1, At, B1); PG8_BAR;
;             PG8_LDA(At, 1, 1); PG8_STAGE(PG8_SA(1, 0), a3, voffA);
;             PG8_BAR; PG8_WAIT_L(0); if (full) PG8_MMA(1, 0, At, B0); PG8_BAR; PG8_SCHED;
;             PG8_STAGE(PG8_SB(1, 1), b3 + hstepB, voffB);
;             PG8_WAIT_V(6); PG8_BAR; if (full) PG8_MMA(1, 1, At, B1); PG8_BAR;
	s_add_u32 s58, s30, 0x80000
	s_addc_u32 s59, s31, 0
	s_add_i32 s60, s54, s43
	v_lshl_add_u64 v[138:139], s[58:59], 0, v[130:131]
	s_mov_b32 m0, s60
	s_nop 0
	global_load_lds_dwordx4 v[138:139], off
	v_lshl_add_u64 v[138:139], s[58:59], 0, v[128:129]
	s_add_i32 m0, s60, 0x2000
	s_nop 0
	global_load_lds_dwordx4 v[138:139], off
	s_waitcnt vmcnt(6)
	s_barrier
	s_setprio 1
	v_mfma_f32_16x16x32_bf16 v[52:55], v[196:199], v[164:167], v[52:55]
	v_mfma_f32_16x16x32_bf16 v[44:47], v[204:207], v[164:167], v[44:47]
	v_mfma_f32_16x16x32_bf16 v[36:39], v[196:199], v[172:175], v[36:39]
	v_mfma_f32_16x16x32_bf16 v[28:31], v[204:207], v[172:175], v[28:31]
	v_mfma_f32_16x16x32_bf16 v[20:23], v[196:199], v[180:183], v[20:23]
	v_mfma_f32_16x16x32_bf16 v[12:15], v[204:207], v[180:183], v[12:15]
	v_mfma_f32_16x16x32_bf16 v[4:7], v[196:199], v[188:191], v[4:7]
	v_mfma_f32_16x16x32_bf16 v[0:3], v[204:207], v[188:191], v[0:3]
	v_mfma_f32_16x16x32_bf16 v[52:55], v[200:203], v[168:171], v[52:55]
	v_mfma_f32_16x16x32_bf16 v[44:47], v[208:211], v[168:171], v[44:47]
	v_mfma_f32_16x16x32_bf16 v[36:39], v[200:203], v[176:179], v[36:39]
	v_mfma_f32_16x16x32_bf16 v[28:31], v[208:211], v[176:179], v[28:31]
	v_mfma_f32_16x16x32_bf16 v[20:23], v[200:203], v[184:187], v[20:23]
	v_mfma_f32_16x16x32_bf16 v[12:15], v[208:211], v[184:187], v[12:15]
	v_mfma_f32_16x16x32_bf16 v[4:7], v[200:203], v[192:195], v[4:7]
	v_mfma_f32_16x16x32_bf16 v[0:3], v[208:211], v[192:195], v[0:3]
	s_setprio 0
	s_add_i32 s58, 0, 0x18000
	v_add_u32_e32 v150, s58, v158
	s_barrier
	ds_read_b128 v[138:141], v150
	ds_read_b128 v[142:145], v150 offset:1024
	ds_read_b128 v[146:149], v150 offset:2048
	ds_read_b128 v[150:153], v150 offset:3072
	s_add_u32 s36, s36, 0x80000
	s_addc_u32 s37, s37, 0
	s_mov_b32 m0, s47
	v_lshl_add_u64 v[196:197], s[36:37], 0, v[130:131]
	ds_read_b128 v[164:167], v161 offset:32768
	ds_read_b128 v[168:171], v161 offset:33792
	ds_read_b128 v[172:175], v161 offset:34816
	ds_read_b128 v[176:179], v161 offset:35840
	ds_read_b128 v[180:183], v161 offset:36864
	ds_read_b128 v[184:187], v161 offset:37888
	ds_read_b128 v[188:191], v161 offset:38912
	ds_read_b128 v[192:195], v161 offset:39936
	global_load_lds_dwordx4 v[196:197], off
	v_lshl_add_u64 v[196:197], s[36:37], 0, v[128:129]
	s_mov_b32 m0, s48
	s_nop 0
	global_load_lds_dwordx4 v[196:197], off
	s_waitcnt lgkmcnt(8)
	s_barrier
	s_waitcnt lgkmcnt(0)
	s_setprio 1
	s_waitcnt lgkmcnt(0)
	v_mfma_f32_16x16x32_bf16 v[124:127], v[138:141], v[164:167], v[124:127]
	v_mfma_f32_16x16x32_bf16 v[120:123], v[146:149], v[164:167], v[120:123]
	v_mfma_f32_16x16x32_bf16 v[116:119], v[138:141], v[172:175], v[116:119]
	v_mfma_f32_16x16x32_bf16 v[104:107], v[146:149], v[172:175], v[104:107]
	v_mfma_f32_16x16x32_bf16 v[96:99], v[138:141], v[180:183], v[96:99]
	v_mfma_f32_16x16x32_bf16 v[88:91], v[146:149], v[180:183], v[88:91]
	v_mfma_f32_16x16x32_bf16 v[80:83], v[138:141], v[188:191], v[80:83]
	v_mfma_f32_16x16x32_bf16 v[72:75], v[146:149], v[188:191], v[72:75]
	v_mfma_f32_16x16x32_bf16 v[124:127], v[142:145], v[168:171], v[124:127]
	v_mfma_f32_16x16x32_bf16 v[120:123], v[150:153], v[168:171], v[120:123]
	v_mfma_f32_16x16x32_bf16 v[116:119], v[142:145], v[176:179], v[116:119]
	v_mfma_f32_16x16x32_bf16 v[104:107], v[150:153], v[176:179], v[104:107]
	v_mfma_f32_16x16x32_bf16 v[96:99], v[142:145], v[184:187], v[96:99]
	v_mfma_f32_16x16x32_bf16 v[88:91], v[150:153], v[184:187], v[88:91]
	v_mfma_f32_16x16x32_bf16 v[80:83], v[142:145], v[192:195], v[80:83]
	v_mfma_f32_16x16x32_bf16 v[72:75], v[150:153], v[192:195], v[72:75]
	s_setprio 0
	s_barrier
	s_add_i32 s36, 0, 0x1c000
	s_add_i32 s37, s58, s43
	v_add_u32_e32 v154, s36, v158
	v_lshl_add_u64 v[156:157], v[156:157], 0, s[8:9]
	s_mov_b32 m0, s37
	ds_read_b128 v[196:199], v154
	ds_read_b128 v[200:203], v154 offset:1024
	ds_read_b128 v[204:207], v154 offset:2048
	ds_read_b128 v[208:211], v154 offset:3072
	global_load_lds_dwordx4 v[156:157], off
	v_lshl_add_u64 v[156:157], v[212:213], 0, s[8:9]
	s_add_i32 m0, s37, 0x2000
	s_nop 0
	global_load_lds_dwordx4 v[156:157], off
	s_barrier
	s_waitcnt lgkmcnt(0)
	s_setprio 1
	s_waitcnt lgkmcnt(0)
	v_mfma_f32_16x16x32_bf16 v[112:115], v[196:199], v[164:167], v[112:115]
	v_mfma_f32_16x16x32_bf16 v[108:111], v[204:207], v[164:167], v[108:111]
	v_mfma_f32_16x16x32_bf16 v[100:103], v[196:199], v[172:175], v[100:103]
	v_mfma_f32_16x16x32_bf16 v[92:95], v[204:207], v[172:175], v[92:95]
	v_mfma_f32_16x16x32_bf16 v[84:87], v[196:199], v[180:183], v[84:87]
	v_mfma_f32_16x16x32_bf16 v[76:79], v[204:207], v[180:183], v[76:79]
	v_mfma_f32_16x16x32_bf16 v[68:71], v[196:199], v[188:191], v[68:71]
	v_mfma_f32_16x16x32_bf16 v[64:67], v[204:207], v[188:191], v[64:67]
	v_mfma_f32_16x16x32_bf16 v[112:115], v[200:203], v[168:171], v[112:115]
	v_mfma_f32_16x16x32_bf16 v[108:111], v[208:211], v[168:171], v[108:111]
	v_mfma_f32_16x16x32_bf16 v[100:103], v[200:203], v[176:179], v[100:103]
	v_mfma_f32_16x16x32_bf16 v[92:95], v[208:211], v[176:179], v[92:95]
	v_mfma_f32_16x16x32_bf16 v[84:87], v[200:203], v[184:187], v[84:87]
	v_mfma_f32_16x16x32_bf16 v[76:79], v[208:211], v[184:187], v[76:79]
	v_mfma_f32_16x16x32_bf16 v[68:71], v[200:203], v[192:195], v[68:71]
	v_mfma_f32_16x16x32_bf16 v[64:67], v[208:211], v[192:195], v[64:67]
	s_setprio 0
	s_mov_b32 m0, s49
	v_lshl_add_u64 v[156:157], v[214:215], 0, s[8:9]
	s_barrier
	ds_read_b128 v[164:167], v161 offset:49152
	ds_read_b128 v[168:171], v161 offset:50176
	ds_read_b128 v[172:175], v161 offset:51200
	ds_read_b128 v[176:179], v161 offset:52224
	ds_read_b128 v[180:183], v161 offset:53248
	ds_read_b128 v[184:187], v161 offset:54272
	ds_read_b128 v[188:191], v161 offset:55296
	ds_read_b128 v[192:195], v161 offset:56320
	global_load_lds_dwordx4 v[156:157], off
	v_lshl_add_u64 v[156:157], v[216:217], 0, s[8:9]
	s_mov_b32 m0, s50
	s_nop 0
	global_load_lds_dwordx4 v[156:157], off
	s_barrier
; DI u32x2 pk4(f32x4 v) { u32x2 r; r.x = pk2(v[0], v[1]); r.y = pk2(v[2], v[3]); return r; }
; DI float silu_f(float x) { return x * __builtin_amdgcn_rcpf(1.f + __builtin_amdgcn_exp2f(-1.4426950409f * x)); }
; #define PG8_STAGE(bufoff, gbase, voff) do { _Pragma("unroll") for (int _i = 0; _i < 2; ++_i) \
;         __builtin_amdgcn_global_load_lds((const unsigned*)((const char*)(gbase) + (voff)[_i]), (LAS unsigned*)(lds + (bufoff) + ldsw + _i * 8192), 16, 0, 0); } while (0)
; #define PG8_LDA(dst, b, h) do { _Pragma("unroll") for (int m = 0; m < 4; ++m) _Pragma("unroll") for (int k = 0; k < 2; ++k) dst[m][k] = *(const LAS bf16x8*)(lds + PG8_SA(b, h) + aoff + m * 2048 + k * 1024); } while (0)
; #define PG8_WAIT_V(n) asm volatile("s_waitcnt vmcnt(" #n ")" ::: "memory")
; #define PG8_WAIT_L(n) asm volatile("s_waitcnt lgkmcnt(" #n ")" ::: "memory")
; template <class Epi>
; DI void gemm_phase(LAS unsigned char* lds, int wid, int K, int lda, int ldb, bool bperm, const Sched3& S, const Epi& E) {
;     ...
;             PG8_LDB(B0, 1, 0); PG8_SCHED; PG8_LDA(At, 1, 0); PG8_STAGE(PG8_SA(0, 1), a2 + h2, voffA);
;             PG8_WAIT_L(8); PG8_BAR; PG8_WAIT_L(0); PG8_MMA(0, 0, At, B0); PG8_BAR; PG8_SCHED;
;             PG8_LDB(B1, 1, 1); PG8_STAGE(PG8_SB(1, 0), b3, voffB);
;             PG8_BAR; PG8_WAIT_L(0); PG8_MMA(0, 1, At, B1); PG8_BAR;
;             PG8_LDA(At, 1, 1); PG8_STAGE(PG8_SA(1, 0), a3, voffA);
;             PG8_BAR; PG8_WAIT_L(0); if (full) PG8_MMA(1, 0, At, B0); PG8_BAR; PG8_SCHED;
;             PG8_STAGE(PG8_SB(1, 1), b3 + hstepB, voffB);
;             PG8_WAIT_V(6); PG8_BAR; if (full) PG8_MMA(1, 1, At, B1); PG8_BAR;
;     DI void operator()(const Acc& acc, const Unit& u, int wr, int wc, int fr, int fq) const {
;     ...
;             LOAD_ROW_RS(rsv, SSQ(PH == 5 ? 2 : 6), 1.f / 2048.f);
;             const int ac0 = u.pn * 128 + wc * 32 + 8 * fq;
;             ROWS8 { const int r = row0 + ai * HALF + m * 16; const float rs = rsv[ai][m];
;                 u32x4 w;
; #pragma unroll
;                 for (int bj = 0; bj < 2; ++bj) { const f32x4 g = acc[ai][bj][m][0] * rs, uu = acc[ai][bj][m][1] * rs;
;                     f32x4 a; a[0] = silu_f(g[0]) * uu[0]; a[1] = silu_f(g[1]) * uu[1]; a[2] = silu_f(g[2]) * uu[2]; a[3] = silu_f(g[3]) * uu[3];
;                     const u32x2 h = pk4(a); if (bj == 0) { w.x = h.x; w.y = h.y; } else { w.z = h.x; w.w = h.y; } }
	s_waitcnt lgkmcnt(0)
	s_setprio 1
	s_waitcnt lgkmcnt(0)
	v_mfma_f32_16x16x32_bf16 v[60:63], v[138:141], v[164:167], v[60:63]
	v_mfma_f32_16x16x32_bf16 v[56:59], v[146:149], v[164:167], v[56:59]
	v_mfma_f32_16x16x32_bf16 v[48:51], v[138:141], v[172:175], v[48:51]
	v_mfma_f32_16x16x32_bf16 v[40:43], v[146:149], v[172:175], v[40:43]
	v_mfma_f32_16x16x32_bf16 v[32:35], v[138:141], v[180:183], v[32:35]
	v_mfma_f32_16x16x32_bf16 v[24:27], v[146:149], v[180:183], v[24:27]
	v_mfma_f32_16x16x32_bf16 v[16:19], v[138:141], v[188:191], v[16:19]
	v_mfma_f32_16x16x32_bf16 v[8:11], v[146:149], v[188:191], v[8:11]
	v_mfma_f32_16x16x32_bf16 v[60:63], v[142:145], v[168:171], v[60:63]
	v_mfma_f32_16x16x32_bf16 v[56:59], v[150:153], v[168:171], v[56:59]
	v_mfma_f32_16x16x32_bf16 v[48:51], v[142:145], v[176:179], v[48:51]
	v_mfma_f32_16x16x32_bf16 v[40:43], v[150:153], v[176:179], v[40:43]
	v_mfma_f32_16x16x32_bf16 v[32:35], v[142:145], v[184:187], v[32:35]
	v_mfma_f32_16x16x32_bf16 v[24:27], v[150:153], v[184:187], v[24:27]
	v_mfma_f32_16x16x32_bf16 v[16:19], v[142:145], v[192:195], v[16:19]
	v_mfma_f32_16x16x32_bf16 v[8:11], v[150:153], v[192:195], v[8:11]
	s_setprio 0
	s_barrier
	s_add_u32 s30, s30, 0x80080
	s_addc_u32 s31, s31, 0
	s_add_i32 s36, s36, s43
	v_lshl_add_u64 v[138:139], s[30:31], 0, v[130:131]
	s_mov_b32 m0, s36
	s_nop 0
	global_load_lds_dwordx4 v[138:139], off
	v_lshl_add_u64 v[138:139], s[30:31], 0, v[128:129]
	s_add_i32 m0, s36, 0x2000
	s_nop 0
	global_load_lds_dwordx4 v[138:139], off
	s_waitcnt vmcnt(6)
	s_barrier
	s_setprio 1
	v_mfma_f32_16x16x32_bf16 v[52:55], v[196:199], v[164:167], v[52:55]
	v_mfma_f32_16x16x32_bf16 v[44:47], v[204:207], v[164:167], v[44:47]
	v_mfma_f32_16x16x32_bf16 v[36:39], v[196:199], v[172:175], v[36:39]
	v_mfma_f32_16x16x32_bf16 v[28:31], v[204:207], v[172:175], v[28:31]
	v_mfma_f32_16x16x32_bf16 v[20:23], v[196:199], v[180:183], v[20:23]
	v_mfma_f32_16x16x32_bf16 v[12:15], v[204:207], v[180:183], v[12:15]
	v_mfma_f32_16x16x32_bf16 v[4:7], v[196:199], v[188:191], v[4:7]
	v_mfma_f32_16x16x32_bf16 v[0:3], v[204:207], v[188:191], v[0:3]
	v_mfma_f32_16x16x32_bf16 v[52:55], v[200:203], v[168:171], v[52:55]
	v_mfma_f32_16x16x32_bf16 v[44:47], v[208:211], v[168:171], v[44:47]
	v_mfma_f32_16x16x32_bf16 v[36:39], v[200:203], v[176:179], v[36:39]
	v_mfma_f32_16x16x32_bf16 v[28:31], v[208:211], v[176:179], v[28:31]
	v_mfma_f32_16x16x32_bf16 v[20:23], v[200:203], v[184:187], v[20:23]
	v_mfma_f32_16x16x32_bf16 v[12:15], v[208:211], v[184:187], v[12:15]
	v_mfma_f32_16x16x32_bf16 v[4:7], v[200:203], v[192:195], v[4:7]
	v_mfma_f32_16x16x32_bf16 v[0:3], v[208:211], v[192:195], v[0:3]
	s_setprio 0
	s_add_i32 s57, s57, 2
	s_add_u32 s28, s28, 0x100
	s_addc_u32 s29, s29, 0
	s_add_u32 s15, s15, 0x100
	s_addc_u32 s17, s17, 0
	s_cmp_gt_u32 s57, 29
	s_barrier
	s_cbranch_scc0 .LBB0_705
	v_lshl_add_u32 v142, s22, 8, v155
	v_or_b32_e32 v156, 16, v142
	v_ashrrev_i32_e32 v157, 31, v156
	v_or_b32_e32 v152, 32, v142
	v_or_b32_e32 v150, 48, v142
	v_lshl_add_u64 v[138:139], v[156:157], 2, s[10:11]
	v_ashrrev_i32_e32 v153, 31, v152
	v_ashrrev_i32_e32 v151, 31, v150
	v_ashrrev_i32_e32 v143, 31, v142
	v_lshl_add_u64 v[140:141], v[152:153], 2, s[10:11]
	v_lshl_add_u64 v[144:145], v[150:151], 2, s[10:11]
	v_lshl_add_u64 v[146:147], v[142:143], 2, s[10:11]
	v_add_u32_e32 v148, 0x80, v142
	v_add_u32_e32 v146, 0x90, v142
	v_add_u32_e32 v144, 0xa0, v142
	v_add_u32_e32 v138, 0xb0, v142
	v_ashrrev_i32_e32 v149, 31, v148
	v_ashrrev_i32_e32 v147, 31, v146
	v_ashrrev_i32_e32 v145, 31, v144
	v_ashrrev_i32_e32 v139, 31, v138
	v_lshl_add_u64 v[140:141], v[148:149], 2, s[10:11]
	v_lshl_add_u64 v[164:165], v[146:147], 2, s[10:11]
	v_lshl_add_u64 v[166:167], v[144:145], 2, s[10:11]
	v_lshl_add_u64 v[168:169], v[138:139], 2, s[10:11]
	v_lshl_add_u32 v164, s56, 7, v159
	v_mov_b64_e32 v[140:141], s[12:13]
	v_ashrrev_i32_e32 v165, 31, v164
	v_mad_i64_i32 v[166:167], s[24:25], v142, s55, v[140:141]
	v_lshlrev_b64 v[142:143], 1, v[164:165]
	v_lshl_add_u64 v[164:165], v[166:167], 0, v[142:143]
	s_and_b64 vcc, exec, s[2:3]
	s_mov_b32 s56, s14
	s_mov_b32 s22, s16
	s_mov_b64 s[30:31], s[18:19]
	s_mov_b64 s[28:29], s[20:21]
	v_mov_b32_e32 v151, v221
	v_mov_b32_e32 v153, v222
	v_mov_b32_e32 v154, v223
	v_mov_b32_e32 v157, v220
	v_mov_b32_e32 v139, v224
	v_mov_b32_e32 v145, v225
	v_mov_b32_e32 v147, v226
	v_mov_b32_e32 v149, v227
	v_fmamk_f32 v151, v151, 0x3a000000, v163
	v_rsq_f32_e32 v168, v151
	v_fmamk_f32 v153, v153, 0x3a000000, v163
	v_fmamk_f32 v157, v157, 0x3a000000, v163
	v_rsq_f32_e32 v166, v157
	v_rsq_f32_e32 v170, v153
	v_pk_mul_f32 v[118:119], v[118:119], v[168:169] op_sel_hi:[1,0]
	v_pk_mul_f32 v[116:117], v[116:117], v[168:169] op_sel_hi:[1,0]
	v_pk_mul_f32 v[126:127], v[126:127], v[166:167] op_sel_hi:[1,0]
	v_pk_mul_f32 v[124:125], v[124:125], v[166:167] op_sel_hi:[1,0]
	v_pk_mul_f32 v[114:115], v[114:115], v[166:167] op_sel_hi:[1,0]
	v_pk_mul_f32 v[112:113], v[112:113], v[166:167] op_sel_hi:[1,0]
	v_pk_mul_f32 v[122:123], v[122:123], v[166:167] op_sel_hi:[1,0]
	v_pk_mul_f32 v[120:121], v[120:121], v[166:167] op_sel_hi:[1,0]
	v_pk_mul_f32 v[110:111], v[110:111], v[166:167] op_sel_hi:[1,0]
	v_pk_mul_f32 v[108:109], v[108:109], v[166:167] op_sel_hi:[1,0]
	v_mul_f32_e32 v151, 0xbfb8aa3b, v124
	v_mul_f32_e32 v153, 0xbfb8aa3b, v125
	v_mul_f32_e32 v157, 0xbfb8aa3b, v126
	v_mul_f32_e32 v166, 0xbfb8aa3b, v127
	v_mul_f32_e32 v167, 0xbfb8aa3b, v112
	v_mul_f32_e32 v169, 0xbfb8aa3b, v113
	v_mul_f32_e32 v171, 0xbfb8aa3b, v114
	v_mul_f32_e32 v172, 0xbfb8aa3b, v115
	v_exp_f32_e32 v151, v151
	v_exp_f32_e32 v153, v153
	v_exp_f32_e32 v157, v157
	v_exp_f32_e32 v166, v166
; DI u32x2 pk4(f32x4 v) { u32x2 r; r.x = pk2(v[0], v[1]); r.y = pk2(v[2], v[3]); return r; }
; DI float silu_f(float x) { return x * __builtin_amdgcn_rcpf(1.f + __builtin_amdgcn_exp2f(-1.4426950409f * x)); }
; #define ROWS8 _Pragma("unroll") for (int ai = 0; ai < 2; ++ai) _Pragma("unroll") for (int m = 0; m < 4; ++m) if (ai == 0 || !hf)
;     DI void operator()(const Acc& acc, const Unit& u, int wr, int wc, int fr, int fq) const {
;     ...
;             ROWS8 { const int r = row0 + ai * HALF + m * 16; const float rs = rsv[ai][m];
;                 u32x4 w;
; #pragma unroll
;                 for (int bj = 0; bj < 2; ++bj) { const f32x4 g = acc[ai][bj][m][0] * rs, uu = acc[ai][bj][m][1] * rs;
;                     f32x4 a; a[0] = silu_f(g[0]) * uu[0]; a[1] = silu_f(g[1]) * uu[1]; a[2] = silu_f(g[2]) * uu[2]; a[3] = silu_f(g[3]) * uu[3];
;                     const u32x2 h = pk4(a); if (bj == 0) { w.x = h.x; w.y = h.y; } else { w.z = h.x; w.w = h.y; } }
;                 *(u32x4*)(WSB(OFF_ACT) + (size_t)r * DFF + ac0) = w;
	v_exp_f32_e32 v167, v167
	v_exp_f32_e32 v169, v169
	v_exp_f32_e32 v171, v171
	v_exp_f32_e32 v172, v172
	v_mul_f32_e32 v173, 0xbfb8aa3b, v116
	v_exp_f32_e32 v178, v173
	v_add_f32_e32 v151, 1.0, v151
	v_add_f32_e32 v153, 1.0, v153
	v_add_f32_e32 v157, 1.0, v157
	v_add_f32_e32 v173, 1.0, v166
	v_add_f32_e32 v174, 1.0, v167
	v_add_f32_e32 v169, 1.0, v169
	v_add_f32_e32 v171, 1.0, v171
	v_add_f32_e32 v177, 1.0, v172
	v_rcp_f32_e32 v166, v151
	v_rcp_f32_e32 v167, v153
	v_rcp_f32_e32 v172, v157
	v_rcp_f32_e32 v173, v173
	v_rcp_f32_e32 v174, v174
	v_rcp_f32_e32 v175, v169
	v_rcp_f32_e32 v176, v171
	v_rcp_f32_e32 v177, v177
	v_pk_mul_f32 v[124:125], v[124:125], v[166:167]
	v_pk_mul_f32 v[126:127], v[126:127], v[172:173]
	v_pk_mul_f32 v[112:113], v[112:113], v[174:175]
	v_pk_mul_f32 v[114:115], v[114:115], v[176:177]
	v_pk_mul_f32 v[120:121], v[120:121], v[124:125]
	v_pk_mul_f32 v[122:123], v[122:123], v[126:127]
	v_pk_mul_f32 v[112:113], v[108:109], v[112:113]
	v_pk_mul_f32 v[114:115], v[110:111], v[114:115]
	v_cvt_pk_bf16_f32 v108, v120, v121
	v_cvt_pk_bf16_f32 v109, v122, v123
	v_cvt_pk_bf16_f32 v110, v112, v113
	v_cvt_pk_bf16_f32 v111, v114, v115
	global_store_dwordx4 v[164:165], v[108:111], off sc1
	v_pk_mul_f32 v[104:105], v[104:105], v[168:169] op_sel_hi:[1,0]
	v_pk_mul_f32 v[106:107], v[106:107], v[168:169] op_sel_hi:[1,0]
	v_mul_f32_e32 v108, 0xbfb8aa3b, v117
	v_exp_f32_e32 v109, v108
	v_mul_f32_e32 v110, 0xbfb8aa3b, v118
	v_mul_f32_e32 v111, 0xbfb8aa3b, v119
	v_exp_f32_e32 v110, v110
	v_exp_f32_e32 v111, v111
	v_add_f32_e32 v108, 1.0, v178
	v_add_f32_e32 v109, 1.0, v109
	v_rcp_f32_e32 v108, v108
	v_rcp_f32_e32 v109, v109
	v_add_f32_e32 v110, 1.0, v110
	v_add_f32_e32 v111, 1.0, v111
	v_rcp_f32_e32 v110, v110
	v_rcp_f32_e32 v111, v111
	v_pk_mul_f32 v[108:109], v[116:117], v[108:109]
	v_pk_mul_f32 v[100:101], v[100:101], v[168:169] op_sel_hi:[1,0]
	v_pk_mul_f32 v[104:105], v[104:105], v[108:109]
	v_pk_mul_f32 v[108:109], v[118:119], v[110:111]
	v_cvt_pk_bf16_f32 v104, v104, v105
	v_pk_mul_f32 v[106:107], v[106:107], v[108:109]
	v_pk_mul_f32 v[102:103], v[102:103], v[168:169] op_sel_hi:[1,0]
	v_cvt_pk_bf16_f32 v105, v106, v107
	v_mul_f32_e32 v106, 0xbfb8aa3b, v100
	v_mul_f32_e32 v107, 0xbfb8aa3b, v101
	v_exp_f32_e32 v106, v106
	v_exp_f32_e32 v107, v107
	v_mul_f32_e32 v108, 0xbfb8aa3b, v102
	v_mul_f32_e32 v109, 0xbfb8aa3b, v103
	v_exp_f32_e32 v108, v108
	v_exp_f32_e32 v109, v109
	v_add_f32_e32 v106, 1.0, v106
	v_add_f32_e32 v107, 1.0, v107
	v_rcp_f32_e32 v106, v106
	v_rcp_f32_e32 v107, v107
	v_add_f32_e32 v108, 1.0, v108
	v_add_f32_e32 v109, 1.0, v109
	v_rcp_f32_e32 v108, v108
	v_rcp_f32_e32 v109, v109
	v_pk_mul_f32 v[92:93], v[92:93], v[168:169] op_sel_hi:[1,0]
	v_pk_mul_f32 v[100:101], v[100:101], v[106:107]
	v_pk_mul_f32 v[94:95], v[94:95], v[168:169] op_sel_hi:[1,0]
	v_pk_mul_f32 v[92:93], v[92:93], v[100:101]
	v_pk_mul_f32 v[100:101], v[102:103], v[108:109]
	v_cvt_pk_bf16_f32 v106, v92, v93
	v_pk_mul_f32 v[94:95], v[94:95], v[100:101]
	v_mad_i64_i32 v[92:93], s[24:25], v156, s55, v[140:141]
	v_cvt_pk_bf16_f32 v107, v94, v95
	v_lshl_add_u64 v[92:93], v[92:93], 0, v[142:143]
	global_store_dwordx4 v[92:93], v[104:107], off sc1
	v_pk_mul_f32 v[92:93], v[98:99], v[170:171] op_sel_hi:[1,0]
	v_pk_mul_f32 v[94:95], v[96:97], v[170:171] op_sel_hi:[1,0]
	v_mul_f32_e32 v98, 0xbfb8aa3b, v92
	v_mul_f32_e32 v96, 0xbfb8aa3b, v94
	v_mul_f32_e32 v97, 0xbfb8aa3b, v95
	v_mul_f32_e32 v99, 0xbfb8aa3b, v93
	v_exp_f32_e32 v96, v96
	v_exp_f32_e32 v97, v97
	v_exp_f32_e32 v98, v98
	v_exp_f32_e32 v99, v99
	v_add_f32_e32 v96, 1.0, v96
	v_add_f32_e32 v97, 1.0, v97
	v_add_f32_e32 v98, 1.0, v98
	v_add_f32_e32 v99, 1.0, v99
	v_rcp_f32_e32 v96, v96
	v_rcp_f32_e32 v97, v97
	v_rcp_f32_e32 v98, v98
	v_rcp_f32_e32 v99, v99
	v_pk_mul_f32 v[90:91], v[90:91], v[170:171] op_sel_hi:[1,0]
	v_pk_mul_f32 v[88:89], v[88:89], v[170:171] op_sel_hi:[1,0]
	v_pk_mul_f32 v[94:95], v[94:95], v[96:97]
	v_pk_mul_f32 v[92:93], v[92:93], v[98:99]
	v_pk_mul_f32 v[88:89], v[88:89], v[94:95]
	v_pk_mul_f32 v[90:91], v[90:91], v[92:93]
	v_pk_mul_f32 v[84:85], v[84:85], v[170:171] op_sel_hi:[1,0]
	v_cvt_pk_bf16_f32 v88, v88, v89
	v_cvt_pk_bf16_f32 v89, v90, v91
	v_pk_mul_f32 v[86:87], v[86:87], v[170:171] op_sel_hi:[1,0]
	v_mul_f32_e32 v90, 0xbfb8aa3b, v84
	v_mul_f32_e32 v91, 0xbfb8aa3b, v85
	v_exp_f32_e32 v90, v90
	v_exp_f32_e32 v91, v91
	v_mul_f32_e32 v92, 0xbfb8aa3b, v86
	v_mul_f32_e32 v93, 0xbfb8aa3b, v87
	v_exp_f32_e32 v92, v92
	v_exp_f32_e32 v93, v93
	v_add_f32_e32 v90, 1.0, v90
	v_add_f32_e32 v91, 1.0, v91
	v_rcp_f32_e32 v90, v90
	v_rcp_f32_e32 v91, v91
	v_add_f32_e32 v92, 1.0, v92
	v_add_f32_e32 v93, 1.0, v93
	v_rcp_f32_e32 v92, v92
	v_rcp_f32_e32 v93, v93
	v_fmamk_f32 v154, v154, 0x3a000000, v163
	v_rsq_f32_e32 v154, v154
	v_pk_mul_f32 v[76:77], v[76:77], v[170:171] op_sel_hi:[1,0]
	v_pk_mul_f32 v[84:85], v[84:85], v[90:91]
	v_pk_mul_f32 v[78:79], v[78:79], v[170:171] op_sel_hi:[1,0]
	v_pk_mul_f32 v[76:77], v[76:77], v[84:85]
	v_pk_mul_f32 v[84:85], v[86:87], v[92:93]
	v_cvt_pk_bf16_f32 v90, v76, v77
	v_pk_mul_f32 v[78:79], v[78:79], v[84:85]
	v_mad_i64_i32 v[76:77], s[24:25], v152, s55, v[140:141]
	v_cvt_pk_bf16_f32 v91, v78, v79
	v_lshl_add_u64 v[76:77], v[76:77], 0, v[142:143]
	global_store_dwordx4 v[76:77], v[88:91], off sc1
	v_pk_mul_f32 v[76:77], v[82:83], v[154:155] op_sel_hi:[1,0]
	v_pk_mul_f32 v[78:79], v[80:81], v[154:155] op_sel_hi:[1,0]
	v_mul_f32_e32 v82, 0xbfb8aa3b, v76
	v_mul_f32_e32 v80, 0xbfb8aa3b, v78
	v_mul_f32_e32 v81, 0xbfb8aa3b, v79
	v_mul_f32_e32 v83, 0xbfb8aa3b, v77
	v_exp_f32_e32 v80, v80
	v_exp_f32_e32 v81, v81
	v_exp_f32_e32 v82, v82
	v_exp_f32_e32 v83, v83
; DI u32x2 pk4(f32x4 v) { u32x2 r; r.x = pk2(v[0], v[1]); r.y = pk2(v[2], v[3]); return r; }
; DI float silu_f(float x) { return x * __builtin_amdgcn_rcpf(1.f + __builtin_amdgcn_exp2f(-1.4426950409f * x)); }
; #define ROWS8 _Pragma("unroll") for (int ai = 0; ai < 2; ++ai) _Pragma("unroll") for (int m = 0; m < 4; ++m) if (ai == 0 || !hf)
;     DI void operator()(const Acc& acc, const Unit& u, int wr, int wc, int fr, int fq) const {
;     ...
;             ROWS8 { const int r = row0 + ai * HALF + m * 16; const float rs = rsv[ai][m];
;                 u32x4 w;
; #pragma unroll
;                 for (int bj = 0; bj < 2; ++bj) { const f32x4 g = acc[ai][bj][m][0] * rs, uu = acc[ai][bj][m][1] * rs;
;                     f32x4 a; a[0] = silu_f(g[0]) * uu[0]; a[1] = silu_f(g[1]) * uu[1]; a[2] = silu_f(g[2]) * uu[2]; a[3] = silu_f(g[3]) * uu[3];
;                     const u32x2 h = pk4(a); if (bj == 0) { w.x = h.x; w.y = h.y; } else { w.z = h.x; w.w = h.y; } }
;                 *(u32x4*)(WSB(OFF_ACT) + (size_t)r * DFF + ac0) = w;
	v_add_f32_e32 v80, 1.0, v80
	v_add_f32_e32 v81, 1.0, v81
	v_add_f32_e32 v82, 1.0, v82
	v_add_f32_e32 v83, 1.0, v83
	v_rcp_f32_e32 v80, v80
	v_rcp_f32_e32 v81, v81
	v_rcp_f32_e32 v82, v82
	v_rcp_f32_e32 v83, v83
	v_pk_mul_f32 v[74:75], v[74:75], v[154:155] op_sel_hi:[1,0]
	v_pk_mul_f32 v[72:73], v[72:73], v[154:155] op_sel_hi:[1,0]
	v_pk_mul_f32 v[78:79], v[78:79], v[80:81]
	v_pk_mul_f32 v[76:77], v[76:77], v[82:83]
	v_pk_mul_f32 v[72:73], v[72:73], v[78:79]
	v_pk_mul_f32 v[74:75], v[74:75], v[76:77]
	v_pk_mul_f32 v[68:69], v[68:69], v[154:155] op_sel_hi:[1,0]
	v_cvt_pk_bf16_f32 v72, v72, v73
	v_cvt_pk_bf16_f32 v73, v74, v75
	v_pk_mul_f32 v[70:71], v[70:71], v[154:155] op_sel_hi:[1,0]
	v_mul_f32_e32 v74, 0xbfb8aa3b, v68
	v_mul_f32_e32 v75, 0xbfb8aa3b, v69
	v_exp_f32_e32 v74, v74
	v_exp_f32_e32 v75, v75
	v_mul_f32_e32 v76, 0xbfb8aa3b, v70
	v_mul_f32_e32 v77, 0xbfb8aa3b, v71
	v_exp_f32_e32 v76, v76
	v_exp_f32_e32 v77, v77
	v_add_f32_e32 v74, 1.0, v74
	v_add_f32_e32 v75, 1.0, v75
	v_rcp_f32_e32 v74, v74
	v_rcp_f32_e32 v75, v75
	v_add_f32_e32 v76, 1.0, v76
	v_add_f32_e32 v77, 1.0, v77
	v_rcp_f32_e32 v76, v76
	v_rcp_f32_e32 v77, v77
	v_pk_mul_f32 v[64:65], v[64:65], v[154:155] op_sel_hi:[1,0]
	v_pk_mul_f32 v[68:69], v[68:69], v[74:75]
	v_pk_mul_f32 v[66:67], v[66:67], v[154:155] op_sel_hi:[1,0]
	v_pk_mul_f32 v[64:65], v[64:65], v[68:69]
	v_pk_mul_f32 v[68:69], v[70:71], v[76:77]
	v_cvt_pk_bf16_f32 v74, v64, v65
	v_pk_mul_f32 v[66:67], v[66:67], v[68:69]
	v_mad_i64_i32 v[64:65], s[24:25], v150, s55, v[140:141]
	v_cvt_pk_bf16_f32 v75, v66, v67
	v_fmamk_f32 v66, v139, 0x3a000000, v163
	v_rsq_f32_e32 v68, v66
	v_lshl_add_u64 v[64:65], v[64:65], 0, v[142:143]
	global_store_dwordx4 v[64:65], v[72:75], off sc1
	v_fmamk_f32 v65, v147, 0x3a000000, v163
	v_rsq_f32_e32 v66, v65
	v_fmamk_f32 v65, v145, 0x3a000000, v163
	v_pk_mul_f32 v[60:61], v[60:61], v[68:69] op_sel_hi:[1,0]
	v_rsq_f32_e32 v70, v65
	v_mul_f32_e32 v65, 0xbfb8aa3b, v60
	v_exp_f32_e32 v65, v65
	v_mul_f32_e32 v67, 0xbfb8aa3b, v61
	v_exp_f32_e32 v67, v67
	v_pk_mul_f32 v[62:63], v[62:63], v[68:69] op_sel_hi:[1,0]
	v_add_f32_e32 v65, 1.0, v65
	v_rcp_f32_e32 v72, v65
	v_add_f32_e32 v65, 1.0, v67
	v_mul_f32_e32 v67, 0xbfb8aa3b, v62
	v_pk_mul_f32 v[58:59], v[58:59], v[68:69] op_sel_hi:[1,0]
	v_exp_f32_e32 v67, v67
	v_mul_f32_e32 v69, 0xbfb8aa3b, v63
	v_exp_f32_e32 v69, v69
	v_rcp_f32_e32 v73, v65
	v_add_f32_e32 v65, 1.0, v67
	v_rcp_f32_e32 v74, v65
	v_add_f32_e32 v65, 1.0, v69
	v_rcp_f32_e32 v75, v65
	v_pk_mul_f32 v[56:57], v[56:57], v[68:69] op_sel_hi:[1,0]
	v_pk_mul_f32 v[60:61], v[60:61], v[72:73]
	v_pk_mul_f32 v[52:53], v[52:53], v[68:69] op_sel_hi:[1,0]
	v_pk_mul_f32 v[56:57], v[56:57], v[60:61]
	v_pk_mul_f32 v[60:61], v[62:63], v[74:75]
	v_cvt_pk_bf16_f32 v56, v56, v57
	v_pk_mul_f32 v[58:59], v[58:59], v[60:61]
	v_pk_mul_f32 v[54:55], v[54:55], v[68:69] op_sel_hi:[1,0]
	v_cvt_pk_bf16_f32 v57, v58, v59
	v_mul_f32_e32 v58, 0xbfb8aa3b, v52
	v_mul_f32_e32 v59, 0xbfb8aa3b, v53
	v_exp_f32_e32 v58, v58
	v_exp_f32_e32 v59, v59
	v_mul_f32_e32 v60, 0xbfb8aa3b, v54
	v_mul_f32_e32 v61, 0xbfb8aa3b, v55
	v_exp_f32_e32 v60, v60
	v_exp_f32_e32 v61, v61
	v_add_f32_e32 v58, 1.0, v58
	v_add_f32_e32 v59, 1.0, v59
	v_rcp_f32_e32 v58, v58
	v_rcp_f32_e32 v59, v59
	v_add_f32_e32 v60, 1.0, v60
	v_add_f32_e32 v61, 1.0, v61
	v_rcp_f32_e32 v60, v60
	v_rcp_f32_e32 v61, v61
	v_pk_mul_f32 v[44:45], v[44:45], v[68:69] op_sel_hi:[1,0]
	v_pk_mul_f32 v[52:53], v[52:53], v[58:59]
	v_pk_mul_f32 v[46:47], v[46:47], v[68:69] op_sel_hi:[1,0]
	v_pk_mul_f32 v[44:45], v[44:45], v[52:53]
	v_pk_mul_f32 v[52:53], v[54:55], v[60:61]
	v_cvt_pk_bf16_f32 v58, v44, v45
	v_pk_mul_f32 v[46:47], v[46:47], v[52:53]
	v_mad_i64_i32 v[44:45], s[24:25], v148, s55, v[140:141]
	v_cvt_pk_bf16_f32 v59, v46, v47
	v_lshl_add_u64 v[44:45], v[44:45], 0, v[142:143]
	global_store_dwordx4 v[44:45], v[56:59], off sc1
	v_pk_mul_f32 v[44:45], v[50:51], v[70:71] op_sel_hi:[1,0]
	v_pk_mul_f32 v[46:47], v[48:49], v[70:71] op_sel_hi:[1,0]
	v_mul_f32_e32 v50, 0xbfb8aa3b, v44
	v_mul_f32_e32 v48, 0xbfb8aa3b, v46
	v_mul_f32_e32 v49, 0xbfb8aa3b, v47
	v_mul_f32_e32 v51, 0xbfb8aa3b, v45
	v_exp_f32_e32 v48, v48
	v_exp_f32_e32 v49, v49
	v_exp_f32_e32 v50, v50
	v_exp_f32_e32 v51, v51
	v_add_f32_e32 v48, 1.0, v48
	v_add_f32_e32 v49, 1.0, v49
	v_add_f32_e32 v50, 1.0, v50
	v_add_f32_e32 v51, 1.0, v51
	v_rcp_f32_e32 v48, v48
	v_rcp_f32_e32 v49, v49
	v_rcp_f32_e32 v50, v50
	v_rcp_f32_e32 v51, v51
	v_pk_mul_f32 v[42:43], v[42:43], v[70:71] op_sel_hi:[1,0]
	v_pk_mul_f32 v[40:41], v[40:41], v[70:71] op_sel_hi:[1,0]
	v_pk_mul_f32 v[46:47], v[46:47], v[48:49]
	v_pk_mul_f32 v[44:45], v[44:45], v[50:51]
	v_pk_mul_f32 v[40:41], v[40:41], v[46:47]
	v_pk_mul_f32 v[42:43], v[42:43], v[44:45]
	v_pk_mul_f32 v[36:37], v[36:37], v[70:71] op_sel_hi:[1,0]
	v_cvt_pk_bf16_f32 v40, v40, v41
	v_cvt_pk_bf16_f32 v41, v42, v43
	v_pk_mul_f32 v[38:39], v[38:39], v[70:71] op_sel_hi:[1,0]
	v_mul_f32_e32 v42, 0xbfb8aa3b, v36
	v_mul_f32_e32 v43, 0xbfb8aa3b, v37
	v_exp_f32_e32 v42, v42
; DI u32x2 pk4(f32x4 v) { u32x2 r; r.x = pk2(v[0], v[1]); r.y = pk2(v[2], v[3]); return r; }
; DI float silu_f(float x) { return x * __builtin_amdgcn_rcpf(1.f + __builtin_amdgcn_exp2f(-1.4426950409f * x)); }
; #define ROWS8 _Pragma("unroll") for (int ai = 0; ai < 2; ++ai) _Pragma("unroll") for (int m = 0; m < 4; ++m) if (ai == 0 || !hf)
; template <class Epi>
; DI void gemm_phase(LAS unsigned char* lds, int wid, int K, int lda, int ldb, bool bperm, const Sched3& S, const Epi& E) {
;     ...
;         E(acc, cur, wr, wc, fr, fq);
;         if (!has_next) break;
;     DI void operator()(const Acc& acc, const Unit& u, int wr, int wc, int fr, int fq) const {
;     ...
;             ROWS8 { const int r = row0 + ai * HALF + m * 16; const float rs = rsv[ai][m];
;                 u32x4 w;
; #pragma unroll
;                 for (int bj = 0; bj < 2; ++bj) { const f32x4 g = acc[ai][bj][m][0] * rs, uu = acc[ai][bj][m][1] * rs;
;                     f32x4 a; a[0] = silu_f(g[0]) * uu[0]; a[1] = silu_f(g[1]) * uu[1]; a[2] = silu_f(g[2]) * uu[2]; a[3] = silu_f(g[3]) * uu[3];
;                     const u32x2 h = pk4(a); if (bj == 0) { w.x = h.x; w.y = h.y; } else { w.z = h.x; w.w = h.y; } }
;                 *(u32x4*)(WSB(OFF_ACT) + (size_t)r * DFF + ac0) = w;
	v_exp_f32_e32 v43, v43
	v_mul_f32_e32 v44, 0xbfb8aa3b, v38
	v_mul_f32_e32 v45, 0xbfb8aa3b, v39
	v_exp_f32_e32 v44, v44
	v_exp_f32_e32 v45, v45
	v_add_f32_e32 v42, 1.0, v42
	v_add_f32_e32 v43, 1.0, v43
	v_rcp_f32_e32 v42, v42
	v_rcp_f32_e32 v43, v43
	v_add_f32_e32 v44, 1.0, v44
	v_add_f32_e32 v45, 1.0, v45
	v_rcp_f32_e32 v44, v44
	v_rcp_f32_e32 v45, v45
	v_pk_mul_f32 v[28:29], v[28:29], v[70:71] op_sel_hi:[1,0]
	v_pk_mul_f32 v[36:37], v[36:37], v[42:43]
	v_pk_mul_f32 v[30:31], v[30:31], v[70:71] op_sel_hi:[1,0]
	v_pk_mul_f32 v[28:29], v[28:29], v[36:37]
	v_pk_mul_f32 v[36:37], v[38:39], v[44:45]
	v_cvt_pk_bf16_f32 v42, v28, v29
	v_pk_mul_f32 v[30:31], v[30:31], v[36:37]
	v_mad_i64_i32 v[28:29], s[24:25], v146, s55, v[140:141]
	v_cvt_pk_bf16_f32 v43, v30, v31
	v_lshl_add_u64 v[28:29], v[28:29], 0, v[142:143]
	global_store_dwordx4 v[28:29], v[40:43], off sc1
	v_pk_mul_f32 v[28:29], v[34:35], v[66:67] op_sel_hi:[1,0]
	v_pk_mul_f32 v[30:31], v[32:33], v[66:67] op_sel_hi:[1,0]
	v_mul_f32_e32 v34, 0xbfb8aa3b, v28
	v_mul_f32_e32 v32, 0xbfb8aa3b, v30
	v_mul_f32_e32 v33, 0xbfb8aa3b, v31
	v_mul_f32_e32 v35, 0xbfb8aa3b, v29
	v_exp_f32_e32 v32, v32
	v_exp_f32_e32 v33, v33
	v_exp_f32_e32 v34, v34
	v_exp_f32_e32 v35, v35
	v_add_f32_e32 v32, 1.0, v32
	v_add_f32_e32 v33, 1.0, v33
	v_add_f32_e32 v34, 1.0, v34
	v_add_f32_e32 v35, 1.0, v35
	v_rcp_f32_e32 v32, v32
	v_rcp_f32_e32 v33, v33
	v_rcp_f32_e32 v34, v34
	v_rcp_f32_e32 v35, v35
	v_pk_mul_f32 v[26:27], v[26:27], v[66:67] op_sel_hi:[1,0]
	v_pk_mul_f32 v[24:25], v[24:25], v[66:67] op_sel_hi:[1,0]
	v_pk_mul_f32 v[30:31], v[30:31], v[32:33]
	v_pk_mul_f32 v[28:29], v[28:29], v[34:35]
	v_pk_mul_f32 v[24:25], v[24:25], v[30:31]
	v_pk_mul_f32 v[26:27], v[26:27], v[28:29]
	v_pk_mul_f32 v[20:21], v[20:21], v[66:67] op_sel_hi:[1,0]
	v_cvt_pk_bf16_f32 v24, v24, v25
	v_cvt_pk_bf16_f32 v25, v26, v27
	v_pk_mul_f32 v[22:23], v[22:23], v[66:67] op_sel_hi:[1,0]
	v_mul_f32_e32 v26, 0xbfb8aa3b, v20
	v_mul_f32_e32 v27, 0xbfb8aa3b, v21
	v_exp_f32_e32 v26, v26
	v_exp_f32_e32 v27, v27
	v_mul_f32_e32 v28, 0xbfb8aa3b, v22
	v_mul_f32_e32 v29, 0xbfb8aa3b, v23
	v_exp_f32_e32 v28, v28
	v_exp_f32_e32 v29, v29
	v_add_f32_e32 v26, 1.0, v26
	v_add_f32_e32 v27, 1.0, v27
	v_rcp_f32_e32 v26, v26
	v_rcp_f32_e32 v27, v27
	v_add_f32_e32 v28, 1.0, v28
	v_add_f32_e32 v29, 1.0, v29
	v_rcp_f32_e32 v28, v28
	v_rcp_f32_e32 v29, v29
	v_fmamk_f32 v64, v149, 0x3a000000, v163
	v_rsq_f32_e32 v64, v64
	v_pk_mul_f32 v[12:13], v[12:13], v[66:67] op_sel_hi:[1,0]
	v_pk_mul_f32 v[20:21], v[20:21], v[26:27]
	v_pk_mul_f32 v[14:15], v[14:15], v[66:67] op_sel_hi:[1,0]
	v_pk_mul_f32 v[12:13], v[12:13], v[20:21]
	v_pk_mul_f32 v[20:21], v[22:23], v[28:29]
	v_cvt_pk_bf16_f32 v26, v12, v13
	v_pk_mul_f32 v[14:15], v[14:15], v[20:21]
	v_mad_i64_i32 v[12:13], s[24:25], v144, s55, v[140:141]
	v_cvt_pk_bf16_f32 v27, v14, v15
	v_lshl_add_u64 v[12:13], v[12:13], 0, v[142:143]
	global_store_dwordx4 v[12:13], v[24:27], off sc1
	v_pk_mul_f32 v[12:13], v[18:19], v[64:65] op_sel_hi:[1,0]
	v_pk_mul_f32 v[14:15], v[16:17], v[64:65] op_sel_hi:[1,0]
	v_mul_f32_e32 v18, 0xbfb8aa3b, v12
	v_mul_f32_e32 v16, 0xbfb8aa3b, v14
	v_mul_f32_e32 v17, 0xbfb8aa3b, v15
	v_mul_f32_e32 v19, 0xbfb8aa3b, v13
	v_exp_f32_e32 v16, v16
	v_exp_f32_e32 v17, v17
	v_exp_f32_e32 v18, v18
	v_exp_f32_e32 v19, v19
	v_add_f32_e32 v16, 1.0, v16
	v_add_f32_e32 v17, 1.0, v17
	v_add_f32_e32 v18, 1.0, v18
	v_add_f32_e32 v19, 1.0, v19
	v_rcp_f32_e32 v16, v16
	v_rcp_f32_e32 v17, v17
	v_rcp_f32_e32 v18, v18
	v_rcp_f32_e32 v19, v19
	v_pk_mul_f32 v[10:11], v[10:11], v[64:65] op_sel_hi:[1,0]
	v_pk_mul_f32 v[8:9], v[8:9], v[64:65] op_sel_hi:[1,0]
	v_pk_mul_f32 v[14:15], v[14:15], v[16:17]
	v_pk_mul_f32 v[12:13], v[12:13], v[18:19]
	v_pk_mul_f32 v[8:9], v[8:9], v[14:15]
	v_pk_mul_f32 v[10:11], v[10:11], v[12:13]
	v_pk_mul_f32 v[4:5], v[4:5], v[64:65] op_sel_hi:[1,0]
	v_cvt_pk_bf16_f32 v8, v8, v9
	v_cvt_pk_bf16_f32 v9, v10, v11
	v_pk_mul_f32 v[6:7], v[6:7], v[64:65] op_sel_hi:[1,0]
	v_mul_f32_e32 v10, 0xbfb8aa3b, v4
	v_mul_f32_e32 v11, 0xbfb8aa3b, v5
	v_exp_f32_e32 v10, v10
	v_exp_f32_e32 v11, v11
	v_mul_f32_e32 v12, 0xbfb8aa3b, v6
	v_mul_f32_e32 v13, 0xbfb8aa3b, v7
	v_exp_f32_e32 v12, v12
	v_exp_f32_e32 v13, v13
	v_add_f32_e32 v10, 1.0, v10
	v_add_f32_e32 v11, 1.0, v11
	v_rcp_f32_e32 v10, v10
	v_rcp_f32_e32 v11, v11
	v_add_f32_e32 v12, 1.0, v12
	v_add_f32_e32 v13, 1.0, v13
	v_rcp_f32_e32 v12, v12
	v_rcp_f32_e32 v13, v13
	v_pk_mul_f32 v[0:1], v[0:1], v[64:65] op_sel_hi:[1,0]
	v_pk_mul_f32 v[4:5], v[4:5], v[10:11]
	v_pk_mul_f32 v[2:3], v[2:3], v[64:65] op_sel_hi:[1,0]
	v_pk_mul_f32 v[0:1], v[0:1], v[4:5]
	v_pk_mul_f32 v[4:5], v[6:7], v[12:13]
	v_cvt_pk_bf16_f32 v10, v0, v1
	v_pk_mul_f32 v[2:3], v[2:3], v[4:5]
	v_mad_i64_i32 v[0:1], s[24:25], v138, s55, v[140:141]
	v_cvt_pk_bf16_f32 v11, v2, v3
	v_lshl_add_u64 v[0:1], v[0:1], 0, v[142:143]
	global_store_dwordx4 v[0:1], v[8:11], off sc1
	s_cbranch_vccz .LBB0_702
	s_waitcnt vmcnt(0)
	s_cmpk_gt_u32 s88, 0xff
	s_cbranch_scc1 .LBB0_709
	s_barrier
